# select search: log of the count started before the exit checks, scalar key/clamp for the transformed probe
# baseline (speedup 1.0000x reference)
; __device__ __forceinline__ float keyval(unsigned k) { return __uint_as_float((k & 0x80000000u) ? (k ^ 0x80000000u) : ~k); }
; __device__ __forceinline__ unsigned valkey(float f) { const unsigned b = __float_as_uint(f); return b ^ ((unsigned)((int)b >> 31) | 0x80000000u); }
; __device__ __forceinline__ void select_query(const unsigned (&u)[64], unsigned vmax, int q, int b, int lane, unsigned* MASKb) {
;     ...
;             if (hi - lo <= 1u) { T = lo; exact = false; break; }
;             const float vlo = keyval(lo), vhi = keyval(hi);
;             const float frac = (it >= 9 && (it & 1)) ? 0.5f : Llo * __builtin_amdgcn_rcpf(Llo + Lhi);
;             unsigned mid = valkey(vlo + frac * (vhi - vlo));
;             if (mid <= lo) mid = lo + 1u;
;             if (mid >= hi) mid = hi - 1u;
;             mid = __builtin_amdgcn_readfirstlane(mid);
;             const int c = count_ge(u, mid, nblk);
;             if (c == 256) { T = mid; exact = true; break; }
;             if (c > 256) { lo = mid; Llo = __log2f((float)c) - L256; if (last == 1) Lhi *= 0.5f; last = 1; }
;             else { hi = mid; Lhi = L256 - __log2f(fmaxf((float)c, 0.5f)); if (last == 2) Llo *= 0.5f; last = 2; }
.Lsqa_red:
	v_add_u32_e32 v0, v0, v34
	v_cmp_le_u32_e64 s[4:5], s14, v138
	v_cmp_le_u32_e64 s[6:7], s14, v140
	v_add_u32_dpp v0, v0, v0 row_shr:1 row_mask:0xf bank_mask:0xf bound_ctrl:1
	v_cmp_le_u32_e64 s[10:11], s14, v139
	v_cmp_le_u32_e64 s[26:27], s14, v141
	v_add_u32_dpp v0, v0, v0 row_shr:2 row_mask:0xf bank_mask:0xf bound_ctrl:1
	s_bcnt1_i32_b64 s28, s[4:5]
	s_bcnt1_i32_b64 s29, s[6:7]
	v_cmp_le_u32_e64 s[4:5], s14, v142
	v_add_u32_dpp v0, v0, v0 row_shr:4 row_mask:0xf bank_mask:0xf bound_ctrl:1
	s_bcnt1_i32_b64 s30, s[10:11]
	s_bcnt1_i32_b64 s31, s[26:27]
	v_cmp_le_u32_e64 s[6:7], s14, v146
	s_add_i32 s28, s28, s29
	v_add_u32_dpp v0, v0, v0 row_shr:8 row_mask:0xf bank_mask:0xf bound_ctrl:1
	v_cmp_le_u32_e64 s[10:11], s14, v143
	v_cmp_le_u32_e64 s[26:27], s14, v147
	s_add_i32 s30, s30, s31
	v_add_u32_dpp v0, v0, v0 row_bcast:15 row_mask:0xa bank_mask:0xf
	s_bcnt1_i32_b64 s29, s[4:5]
	s_bcnt1_i32_b64 s31, s[6:7]
	s_add_i32 s28, s28, s30
	v_add_u32_dpp v0, v0, v0 row_bcast:31 row_mask:0xc bank_mask:0xf
	s_bcnt1_i32_b64 s30, s[10:11]
	s_add_i32 s29, s29, s31
	s_bcnt1_i32_b64 s31, s[26:27]
	s_add_i32 s28, s28, s29
	s_add_i32 s30, s30, s31
	v_readlane_b32 s24, v0, 63
	s_add_i32 s28, s28, s30
	s_add_i32 s24, s24, s28
	s_max_u32 s26, s24, 1
	v_cvt_f32_u32_e32 v191, s26
	s_cmp_lg_u32 s21, 2
	s_cbranch_scc1 .Lsqa_disp
	v_log_f32_e32 v191, v191
	s_cmp_lg_u32 s99, 0
	s_cbranch_scc1 .Lsqa_st2
	s_cmpk_eq_i32 s24, 0x100
	s_cbranch_scc1 .Lsqa_exact
	s_cmpk_gt_i32 s24, 0x100
	s_cselect_b64 vcc, -1, 0
	s_cselect_b32 s13, s14, s13
	s_cselect_b32 s12, s12, s14
	s_cselect_b32 s98, s24, s98
	s_cselect_b32 s15, s15, s24
	s_cselect_b32 s26, 1, 2
	v_cndmask_b32_e32 v192, v192, v88, vcc
	v_cndmask_b32_e32 v193, v88, v193, vcc
	s_cmp_eq_u32 s23, s26
	s_cselect_b32 s27, 0x3f400000, 1.0
	s_mov_b32 s23, s26
	s_add_i32 s22, s22, 1
	v_add_f32_e32 v0, 0xc1000b88, v191
	v_sub_f32_e32 v34, 0x41000b88, v191
	v_mul_f32_e32 v203, s27, v36
	v_mul_f32_e32 v204, s27, v35
	v_cndmask_b32_e32 v35, v204, v0, vcc
	v_cndmask_b32_e32 v36, v34, v203, vcc
.Lsqa_next:
	s_sub_u32 s26, s12, s13
	s_cmp_lt_u32 s26, 2
	s_cbranch_scc1 .Lsqa_collapse
	s_sub_u32 s26, s98, s15
	s_cmp_le_u32 s26, 4
	s_cbranch_scc1 .Lsqa_endg
	s_cmp_eq_u32 s101, 0
	s_cbranch_scc1 .Lsqa_lin
	s_cmp_lt_i32 s22, 9
	s_cbranch_scc0 .Lsqa_lin
	v_add_f32_e32 v191, v35, v36
	v_sub_f32_e32 v34, v193, v192
	v_rcp_f32_e32 v191, v191
	s_lshl_b32 s26, s99, 31
	v_mul_f32_e32 v191, v35, v191
	v_fma_f32 v88, v191, v34, v192
	v_log_f32_e32 v0, v88
	s_add_i32 s27, s13, 1
	v_mul_f32_e32 v0, 0x3f2aaaab, v0
	v_exp_f32_e32 v191, v0
	s_add_i32 s28, s12, -1
	s_sub_i32 s26, 0, s99
	v_readfirstlane_b32 s14, v191
	s_bitset1_b32 s14, 31
	s_xor_b32 s14, s14, s26
	s_max_u32 s14, s14, s27
	s_min_u32 s14, s14, s28
	s_branch .Lsqa_count

; __device__ __forceinline__ float keyval(unsigned k) { return __uint_as_float((k & 0x80000000u) ? (k ^ 0x80000000u) : ~k); }
; __device__ __forceinline__ unsigned valkey(float f) { const unsigned b = __float_as_uint(f); return b ^ ((unsigned)((int)b >> 31) | 0x80000000u); }
; __device__ __forceinline__ void select_query(const unsigned (&u)[64], unsigned vmax, int q, int b, int lane, unsigned* MASKb) {
;     ...
;             if (hi - lo <= 1u) { T = lo; exact = false; break; }
;             const float vlo = keyval(lo), vhi = keyval(hi);
;             const float frac = (it >= 9 && (it & 1)) ? 0.5f : Llo * __builtin_amdgcn_rcpf(Llo + Lhi);
;             unsigned mid = valkey(vlo + frac * (vhi - vlo));
;             if (mid <= lo) mid = lo + 1u;
;             if (mid >= hi) mid = hi - 1u;
;             mid = __builtin_amdgcn_readfirstlane(mid);
;             const int c = count_ge(u, mid, nblk);
;             if (c == 256) { T = mid; exact = true; break; }
;             if (c > 256) { lo = mid; Llo = __log2f((float)c) - L256; if (last == 1) Lhi *= 0.5f; last = 1; }
;             else { hi = mid; Lhi = L256 - __log2f(fmaxf((float)c, 0.5f)); if (last == 2) Llo *= 0.5f; last = 2; }
.Lsqb_red:
	v_add_u32_e32 v138, v138, v140
	v_cmp_le_u32_e64 s[4:5], s14, v98
	v_cmp_le_u32_e64 s[6:7], s14, v107
	v_add_u32_dpp v138, v138, v138 row_shr:1 row_mask:0xf bank_mask:0xf bound_ctrl:1
	v_cmp_le_u32_e64 s[10:11], s14, v99
	v_cmp_le_u32_e64 s[26:27], s14, v108
	v_add_u32_dpp v138, v138, v138 row_shr:2 row_mask:0xf bank_mask:0xf bound_ctrl:1
	s_bcnt1_i32_b64 s28, s[4:5]
	s_bcnt1_i32_b64 s29, s[6:7]
	v_cmp_le_u32_e64 s[4:5], s14, v109
	v_add_u32_dpp v138, v138, v138 row_shr:4 row_mask:0xf bank_mask:0xf bound_ctrl:1
	s_bcnt1_i32_b64 s30, s[10:11]
	s_bcnt1_i32_b64 s31, s[26:27]
	v_cmp_le_u32_e64 s[6:7], s14, v113
	s_add_i32 s28, s28, s29
	v_add_u32_dpp v138, v138, v138 row_shr:8 row_mask:0xf bank_mask:0xf bound_ctrl:1
	v_cmp_le_u32_e64 s[10:11], s14, v110
	v_cmp_le_u32_e64 s[26:27], s14, v114
	s_add_i32 s30, s30, s31
	v_add_u32_dpp v138, v138, v138 row_bcast:15 row_mask:0xa bank_mask:0xf
	s_bcnt1_i32_b64 s29, s[4:5]
	s_bcnt1_i32_b64 s31, s[6:7]
	s_add_i32 s28, s28, s30
	v_add_u32_dpp v138, v138, v138 row_bcast:31 row_mask:0xc bank_mask:0xf
	s_bcnt1_i32_b64 s30, s[10:11]
	s_add_i32 s29, s29, s31
	s_bcnt1_i32_b64 s31, s[26:27]
	s_add_i32 s28, s28, s29
	s_add_i32 s30, s30, s31
	v_readlane_b32 s24, v138, 63
	s_add_i32 s28, s28, s30
	s_add_i32 s24, s24, s28
	s_max_u32 s26, s24, 1
	v_cvt_f32_u32_e32 v142, s26
	s_cmp_lg_u32 s21, 2
	s_cbranch_scc1 .Lsqb_disp
	v_log_f32_e32 v142, v142
	s_cmp_lg_u32 s99, 0
	s_cbranch_scc1 .Lsqb_st2
	s_cmpk_eq_i32 s24, 0x100
	s_cbranch_scc1 .Lsqb_exact
	s_cmpk_gt_i32 s24, 0x100
	s_cselect_b64 vcc, -1, 0
	s_cselect_b32 s13, s14, s13
	s_cselect_b32 s12, s12, s14
	s_cselect_b32 s98, s24, s98
	s_cselect_b32 s15, s15, s24
	s_cselect_b32 s26, 1, 2
	v_cndmask_b32_e32 v76, v76, v146, vcc
	v_cndmask_b32_e32 v77, v146, v77, vcc
	s_cmp_eq_u32 s23, s26
	s_cselect_b32 s27, 0x3f400000, 1.0
	s_mov_b32 s23, s26
	s_add_i32 s22, s22, 1
	v_add_f32_e32 v138, 0xc1000b88, v142
	v_sub_f32_e32 v140, 0x41000b88, v142
	v_mul_f32_e32 v203, s27, v141
	v_mul_f32_e32 v204, s27, v139
	v_cndmask_b32_e32 v139, v204, v138, vcc
	v_cndmask_b32_e32 v141, v140, v203, vcc
.Lsqb_next:
	s_sub_u32 s26, s12, s13
	s_cmp_lt_u32 s26, 2
	s_cbranch_scc1 .Lsqb_collapse
	s_sub_u32 s26, s98, s15
	s_cmp_le_u32 s26, 4
	s_cbranch_scc1 .Lsqb_endg
	s_cmp_eq_u32 s101, 0
	s_cbranch_scc1 .Lsqb_lin
	s_cmp_lt_i32 s22, 9
	s_cbranch_scc0 .Lsqb_lin
	v_add_f32_e32 v142, v139, v141
	v_sub_f32_e32 v140, v77, v76
	v_rcp_f32_e32 v142, v142
	s_lshl_b32 s26, s99, 31
	v_mul_f32_e32 v142, v139, v142
	v_fma_f32 v146, v142, v140, v76
	v_log_f32_e32 v138, v146
	s_add_i32 s27, s13, 1
	v_mul_f32_e32 v138, 0x3f2aaaab, v138
	v_exp_f32_e32 v142, v138
	s_add_i32 s28, s12, -1
	s_sub_i32 s26, 0, s99
	v_readfirstlane_b32 s14, v142
	s_bitset1_b32 s14, 31
	s_xor_b32 s14, s14, s26
	s_max_u32 s14, s14, s27
	s_min_u32 s14, s14, s28
	s_branch .Lsqb_count
